# MLA prompt units: next work-queue index fetched during the last tile (atomic prefetch)
# baseline (speedup 1.0000x reference)
.LBB0_860:
	s_or_b64 exec, exec, s[6:7]
	s_waitcnt lgkmcnt(0)
	v_mov_b32_e32 v0, v210
	s_barrier
	s_load_dwordx4 s[20:23], s[0:1], 0x10
	v_readfirstlane_b32 s4, v0
	s_ashr_i32 s5, s4, 6
	v_and_b32_e32 v1, 31, v0
	s_add_u32 s3, s30, 0x142ec800
	v_lshl_or_b32 v198, s5, 5, v1
	s_addc_u32 s70, s31, 0
	s_ashr_i32 s71, s4, 7
	s_lshl_b32 s5, s5, 1
	s_add_u32 s72, s36, 0x5500000
	s_addc_u32 s73, s37, 0
	s_add_u32 s74, s36, 0x5580000
	s_addc_u32 s75, s37, 0
	s_ashr_i32 s4, s4, 1
	s_and_b32 s62, s4, 0xffffff80
	s_add_u32 s54, s30, 0x143ec800
	v_bfe_u32 v1, v0, 4, 1
	s_addc_u32 s55, s31, 0
	s_add_i32 s76, 0, 0x257c0
	s_movk_i32 s64, 0xff00
	s_mov_b32 s61, 0
	v_cmp_eq_u32_e64 s[6:7], 0, v0
	v_and_or_b32 v199, s5, 6, v1
	v_and_b32_e32 v200, 15, v0
	s_ashr_i32 s63, s62, 31
	v_mov_b32_e32 v193, 0
	v_mov_b32_e32 v201, s76
	s_movk_i32 s77, 0xc00
	s_movk_i32 s78, 0x500
	s_mov_b32 s79, 0x66666667
	s_mov_b32 s65, -1
	s_movk_i32 s80, 0x300
	s_movk_i32 s81, 0xff
	s_movk_i32 s82, 0x100
	s_movk_i32 s83, 0x150
	s_mov_b32 s85, 0xcccccccd
	s_movk_i32 s87, 0x2400
	s_movk_i32 s88, 0x1000
	s_movk_i32 s89, 0xfe0
	s_movk_i32 s90, 0x250
	s_movk_i32 s91, 0xfc0
	v_mbcnt_hi_u32_b32 v211, -1, v254
	v_mov_b32_e32 v202, 0xf149f2ca
	s_mov_b32 s92, 0
	s_branch .LBB0_864

.LBB0_864:
	s_waitcnt lgkmcnt(0)
	s_barrier
	s_and_saveexec_b64 s[8:9], s[6:7]
	s_cbranch_execz .LBB0_868
	s_cmp_eq_u32 s92, 1
	s_cbranch_scc1 .Lpre_have
	s_mov_b64 s[12:13], exec
	v_mbcnt_lo_u32_b32 v0, s12, 0
	v_mbcnt_hi_u32_b32 v0, s13, v0
	v_cmp_eq_u32_e32 vcc, 0, v0
	s_and_saveexec_b64 s[10:11], vcc
	s_cbranch_execz .LBB0_867
	s_bcnt1_i32_b64 s4, s[12:13]
	v_mov_b32_e32 v1, s4
	global_atomic_add v1, v193, v1, s[30:31] sc0

.Lpre_join:
	v_mov_b32_e32 v1, s76
	s_nop 0
	v_add_u32_e32 v0, s4, v0
	ds_write_b32 v1, v0
.LBB0_868:
	s_or_b64 exec, exec, s[8:9]
	s_mov_b32 s92, 0
	s_waitcnt lgkmcnt(0)
	s_barrier
	ds_read_b32 v0, v201
	s_movk_i32 s4, 0x43f
	s_mov_b64 s[8:9], -1
	s_waitcnt lgkmcnt(0)
	v_cmp_lt_i32_e32 vcc, s4, v0
	v_readfirstlane_b32 s33, v0
	s_cbranch_vccnz .LBB0_863
	s_cmp_gt_i32 s33, 63
	s_cbranch_scc0 .LBB0_1017
	s_sub_i32 s4, s33, 64
	s_lshr_b32 s19, s4, 6
	s_sub_i32 s18, 15, s19
	s_lshl_b32 s5, s33, 8
	s_lshl_b32 s4, s18, 8
	s_and_b32 s8, s5, 0x3000
	s_or_b32 s4, s4, s8
	s_and_b32 s46, s33, 15
	v_add_u32_e32 v124, s4, v198
	v_mov_b64_e32 v[0:1], s[42:43]
	v_mov_b32_e32 v6, v210
	v_mad_i64_i32 v[0:1], s[4:5], v124, s77, v[0:1]
	s_mul_i32 s60, s46, 0xc0
	v_lshl_add_u64 v[0:1], v[0:1], 0, s[60:61]
	v_bfe_u32 v7, v6, 5, 1
	v_lshlrev_b32_e32 v192, 4, v7
	v_lshl_add_u64 v[0:1], v[0:1], 0, v[192:193]
	global_load_dwordx4 v[64:67], v[0:1], off
	global_load_dwordx4 v[68:71], v[0:1], off offset:32
	global_load_dwordx4 v[72:75], v[0:1], off offset:64
	global_load_dwordx4 v[76:79], v[0:1], off offset:96
	global_load_dwordx4 v[80:83], v[0:1], off offset:128
	global_load_dwordx4 v[84:87], v[0:1], off offset:160
	s_lshl_b32 s4, s8, 12
	s_add_u32 s4, s58, s4
	s_addc_u32 s5, s59, 0
	s_lshl_b32 s9, s46, 8
	s_add_u32 s66, s4, s9
	s_addc_u32 s67, s5, 0
	s_lshl_b32 s4, s8, 6
	s_add_u32 s68, s3, s4
	v_mul_hi_i32 v0, v6, s79
	s_addc_u32 s69, s70, 0
	v_cmp_gt_i32_e64 s[8:9], s78, v6
	v_lshrrev_b32_e32 v8, 31, v0
	v_ashrrev_i32_e32 v9, 3, v0
	s_and_saveexec_b64 s[10:11], s[8:9]
	s_cbranch_execz .LBB0_876
	v_add_u32_e32 v2, v9, v8
	v_mul_lo_u32 v0, v2, 20
	v_sub_u32_e32 v0, v6, v0
	v_cmp_lt_i32_e32 vcc, 15, v0
	v_ashrrev_i32_e32 v3, 31, v2
	v_lshlrev_b32_e32 v0, 3, v0
	s_and_saveexec_b64 s[4:5], vcc
	s_xor_b64 s[12:13], exec, s[4:5]
	v_lshlrev_b64 v[2:3], 6, v[2:3]
	v_lshl_add_u64 v[2:3], s[68:69], 0, v[2:3]
	v_mov_b32_e32 v1, v193
	v_lshl_add_u64 v[0:1], v[0:1], 1, v[2:3]
	v_lshl_add_u64 v[4:5], v[0:1], 0, s[64:65]
	s_andn2_saveexec_b64 s[12:13], s[12:13]
	v_lshlrev_b64 v[2:3], 12, v[2:3]
	v_lshl_add_u64 v[2:3], s[66:67], 0, v[2:3]
	v_ashrrev_i32_e32 v1, 31, v0
	v_lshl_add_u64 v[4:5], v[0:1], 1, v[2:3]
	s_or_b64 exec, exec, s[12:13]
	global_load_dwordx4 v[88:91], v[4:5], off

.Lpre_have:
	s_waitcnt vmcnt(0)
	v_readfirstlane_b32 s4, v216
	v_mov_b32_e32 v0, 0
	s_branch .Lpre_join

.Lst_a0_nold:
	s_add_i32 s4, s93, 1
	s_cmp_lg_u32 s4, s51
	s_cbranch_scc1 .Lst_noat_0
	s_mov_b32 s92, 1
	s_and_saveexec_b64 s[66:67], s[6:7]
	s_cbranch_execz .Lst_noat2_0
	v_mov_b32_e32 v216, 1
	global_atomic_add v216, v193, v216, s[30:31] sc0
